# RWKV scan pair-decay form: producer pre-scales each token pair (k/W, b/W, W*r | W_A*a_B, W_A*W_B), consumer skips the decay multiply on the pair leader: 8 packed ops + 2 LDS reads fewer per pair
# speedup vs baseline: 1.0047x; 1.0047x over previous
; __device__ __forceinline__ void scan_chain(const Params& p, int l, int chain, unsigned char* lds) {
;     ...
; #pragma unroll
;         for (int e = 0; e < 8; ++e) { kk[e] *= rn; bv[e] = kk[e] * av[e]; kk[e] = -kk[e]; }
;         *(f32x4*)(a0p + 0 * 2048) = (f32x4){dec[0], dec[1], dec[2], dec[3]}; *(f32x4*)(a0p + 0 * 2048 + 4) = (f32x4){dec[4], dec[5], dec[6], dec[7]};
;         *(f32x4*)(a0p + 1 * 2048) = (f32x4){kd[0], kd[1], kd[2], kd[3]};     *(f32x4*)(a0p + 1 * 2048 + 4) = (f32x4){kd[4], kd[5], kd[6], kd[7]};
;         *(f32x4*)(a0p + 2 * 2048) = (f32x4){kk[0], kk[1], kk[2], kk[3]};     *(f32x4*)(a0p + 2 * 2048 + 4) = (f32x4){kk[4], kk[5], kk[6], kk[7]};
;         *(f32x4*)(a0p + 3 * 2048) = (f32x4){bv[0], bv[1], bv[2], bv[3]};     *(f32x4*)(a0p + 3 * 2048 + 4) = (f32x4){bv[4], bv[5], bv[6], bv[7]};
;         *(f32x4*)(a0p + 4 * 2048) = (f32x4){us[0][0], us[0][1], us[0][2], us[0][3]}; *(f32x4*)(a0p + 4 * 2048 + 4) = (f32x4){us[0][4], us[0][5], us[0][6], us[0][7]};
;         *(f32x4*)(a0p + 5 * 2048) = (f32x4){us[2][0], us[2][1], us[2][2], us[2][3]}; *(f32x4*)(a0p + 5 * 2048 + 4) = (f32x4){us[2][4], us[2][5], us[2][6], us[2][7]};
;     ...
;     if (wave >= 4) { load_raw(0, R); process(0, R, 1); }
.LBB0_302:
	s_or_b64 exec, exec, s[0:1]
	s_mov_b32 s100, 0
	v_lshl_add_u32 v126, v237, 5, s100
	v_add_u32_e32 v126, 0xffffe000, v126
	v_xor_b32_e32 v127, 0x100, v126
	s_waitcnt lgkmcnt(0)
	ds_read_b128 v[78:81], v126
	ds_read_b128 v[82:85], v126 offset:16
	ds_read_b128 v[94:97], v126 offset:8192
	ds_read_b128 v[98:101], v126 offset:8208
	ds_read_b128 v[102:105], v126 offset:16384
	ds_read_b128 v[106:109], v126 offset:16400
	ds_read_b128 v[110:113], v126 offset:24576
	ds_read_b128 v[114:117], v126 offset:24592
	ds_read_b128 v[118:121], v126 offset:32768
	ds_read_b128 v[122:125], v126 offset:32784
	ds_read_b128 v[86:89], v127
	ds_read_b128 v[90:93], v127 offset:16
	s_mov_b32 s100, 0xff00ff
	s_mov_b32 s101, 0xff00ff
	s_cmp_lg_u64 s[68:69], 0
	s_cbranch_scc1 .Lpair_fwd_p
	s_not_b64 s[100:101], s[100:101]
.Lpair_fwd_p:
	s_waitcnt lgkmcnt(0)
	v_rcp_f32_e32 v128, v78
	v_cndmask_b32_e64 v130, 1.0, v78, s[100:101]
	v_cndmask_b32_e64 v131, v86, 1.0, s[100:101]
	v_cndmask_b32_e64 v129, 1.0, v128, s[100:101]
	v_mul_f32_e32 v118, v118, v130
	v_mul_f32_e32 v102, v102, v131
	v_mul_f32_e32 v78, v78, v131
	v_mul_f32_e32 v94, v94, v129
	v_mul_f32_e32 v110, v110, v129
	v_rcp_f32_e32 v128, v79
	v_cndmask_b32_e64 v130, 1.0, v79, s[100:101]
	v_cndmask_b32_e64 v131, v87, 1.0, s[100:101]
	v_cndmask_b32_e64 v129, 1.0, v128, s[100:101]
	v_mul_f32_e32 v119, v119, v130
	v_mul_f32_e32 v103, v103, v131
	v_mul_f32_e32 v79, v79, v131
	v_mul_f32_e32 v95, v95, v129
	v_mul_f32_e32 v111, v111, v129
	v_rcp_f32_e32 v128, v80
	v_cndmask_b32_e64 v130, 1.0, v80, s[100:101]
	v_cndmask_b32_e64 v131, v88, 1.0, s[100:101]
	v_cndmask_b32_e64 v129, 1.0, v128, s[100:101]
	v_mul_f32_e32 v120, v120, v130
	v_mul_f32_e32 v104, v104, v131
	v_mul_f32_e32 v80, v80, v131
	v_mul_f32_e32 v96, v96, v129
	v_mul_f32_e32 v112, v112, v129
	v_rcp_f32_e32 v128, v81
	v_cndmask_b32_e64 v130, 1.0, v81, s[100:101]
	v_cndmask_b32_e64 v131, v89, 1.0, s[100:101]
	v_cndmask_b32_e64 v129, 1.0, v128, s[100:101]
	v_mul_f32_e32 v121, v121, v130
	v_mul_f32_e32 v105, v105, v131
	v_mul_f32_e32 v81, v81, v131
	v_mul_f32_e32 v97, v97, v129
	v_mul_f32_e32 v113, v113, v129
	v_rcp_f32_e32 v128, v82
	v_cndmask_b32_e64 v130, 1.0, v82, s[100:101]
	v_cndmask_b32_e64 v131, v90, 1.0, s[100:101]
	v_cndmask_b32_e64 v129, 1.0, v128, s[100:101]
	v_mul_f32_e32 v122, v122, v130
	v_mul_f32_e32 v106, v106, v131
	v_mul_f32_e32 v82, v82, v131
	v_mul_f32_e32 v98, v98, v129
	v_mul_f32_e32 v114, v114, v129
	v_rcp_f32_e32 v128, v83
	v_cndmask_b32_e64 v130, 1.0, v83, s[100:101]
	v_cndmask_b32_e64 v131, v91, 1.0, s[100:101]
	v_cndmask_b32_e64 v129, 1.0, v128, s[100:101]
	v_mul_f32_e32 v123, v123, v130
	v_mul_f32_e32 v107, v107, v131
	v_mul_f32_e32 v83, v83, v131
	v_mul_f32_e32 v99, v99, v129
	v_mul_f32_e32 v115, v115, v129
	v_rcp_f32_e32 v128, v84
	v_cndmask_b32_e64 v130, 1.0, v84, s[100:101]
	v_cndmask_b32_e64 v131, v92, 1.0, s[100:101]
	v_cndmask_b32_e64 v129, 1.0, v128, s[100:101]
	v_mul_f32_e32 v124, v124, v130
	v_mul_f32_e32 v108, v108, v131
	v_mul_f32_e32 v84, v84, v131
	v_mul_f32_e32 v100, v100, v129
	v_mul_f32_e32 v116, v116, v129
	v_rcp_f32_e32 v128, v85
	v_cndmask_b32_e64 v130, 1.0, v85, s[100:101]
	v_cndmask_b32_e64 v131, v93, 1.0, s[100:101]
	v_cndmask_b32_e64 v129, 1.0, v128, s[100:101]
	v_mul_f32_e32 v125, v125, v130
	v_mul_f32_e32 v109, v109, v131
	v_mul_f32_e32 v85, v85, v131
	v_mul_f32_e32 v101, v101, v129
	v_mul_f32_e32 v117, v117, v129
	ds_write_b128 v126, v[78:81]
	ds_write_b128 v126, v[82:85] offset:16
	ds_write_b128 v126, v[94:97] offset:8192
	ds_write_b128 v126, v[98:101] offset:8208
	ds_write_b128 v126, v[102:105] offset:16384
	ds_write_b128 v126, v[106:109] offset:16400
	ds_write_b128 v126, v[110:113] offset:24576
	ds_write_b128 v126, v[114:117] offset:24592
	ds_write_b128 v126, v[118:121] offset:32768
	ds_write_b128 v126, v[122:125] offset:32784
	s_lshl_b32 s6, s4, 9
	s_mov_b32 s7, s5

; __device__ __forceinline__ void scan_chain(const Params& p, int l, int chain, unsigned char* lds) {
;     ...
; #pragma unroll
;         for (int e = 0; e < 8; ++e) { kk[e] *= rn; bv[e] = kk[e] * av[e]; kk[e] = -kk[e]; }
;         *(f32x4*)(a0p + 0 * 2048) = (f32x4){dec[0], dec[1], dec[2], dec[3]}; *(f32x4*)(a0p + 0 * 2048 + 4) = (f32x4){dec[4], dec[5], dec[6], dec[7]};
;         *(f32x4*)(a0p + 1 * 2048) = (f32x4){kd[0], kd[1], kd[2], kd[3]};     *(f32x4*)(a0p + 1 * 2048 + 4) = (f32x4){kd[4], kd[5], kd[6], kd[7]};
;         *(f32x4*)(a0p + 2 * 2048) = (f32x4){kk[0], kk[1], kk[2], kk[3]};     *(f32x4*)(a0p + 2 * 2048 + 4) = (f32x4){kk[4], kk[5], kk[6], kk[7]};
;         *(f32x4*)(a0p + 3 * 2048) = (f32x4){bv[0], bv[1], bv[2], bv[3]};     *(f32x4*)(a0p + 3 * 2048 + 4) = (f32x4){bv[4], bv[5], bv[6], bv[7]};
;         *(f32x4*)(a0p + 4 * 2048) = (f32x4){us[0][0], us[0][1], us[0][2], us[0][3]}; *(f32x4*)(a0p + 4 * 2048 + 4) = (f32x4){us[0][4], us[0][5], us[0][6], us[0][7]};
;         *(f32x4*)(a0p + 5 * 2048) = (f32x4){us[2][0], us[2][1], us[2][2], us[2][3]}; *(f32x4*)(a0p + 5 * 2048 + 4) = (f32x4){us[2][4], us[2][5], us[2][6], us[2][7]};
;     ...
;             if (c > 0) flush(c - 1);
;             if (c + 1 < NC) process(c + 1, R, c + 2);
.LBB0_314:
	s_or_b64 exec, exec, s[0:1]
	s_add_i32 s100, s10, 1
	s_and_b32 s100, s100, 1
	s_mul_i32 s100, s100, 0xc000
	v_lshl_add_u32 v66, v237, 5, s100
	v_add_u32_e32 v66, 0xffffe000, v66
	v_xor_b32_e32 v67, 0x100, v66
	s_waitcnt lgkmcnt(0)
	ds_read_b128 v[18:21], v66
	ds_read_b128 v[22:25], v66 offset:16
	ds_read_b128 v[34:37], v66 offset:8192
	ds_read_b128 v[38:41], v66 offset:8208
	ds_read_b128 v[42:45], v66 offset:16384
	ds_read_b128 v[46:49], v66 offset:16400
	ds_read_b128 v[50:53], v66 offset:24576
	ds_read_b128 v[54:57], v66 offset:24592
	ds_read_b128 v[58:61], v66 offset:32768
	ds_read_b128 v[62:65], v66 offset:32784
	ds_read_b128 v[26:29], v67
	ds_read_b128 v[30:33], v67 offset:16
	s_mov_b32 s100, 0xff00ff
	s_mov_b32 s101, 0xff00ff
	s_cmp_lg_u64 s[68:69], 0
	s_cbranch_scc1 .Lpair_fwd_l
	s_not_b64 s[100:101], s[100:101]
.Lpair_fwd_l:
	s_waitcnt lgkmcnt(0)
	v_rcp_f32_e32 v68, v18
	v_cndmask_b32_e64 v70, 1.0, v18, s[100:101]
	v_cndmask_b32_e64 v71, v26, 1.0, s[100:101]
	v_cndmask_b32_e64 v69, 1.0, v68, s[100:101]
	v_mul_f32_e32 v58, v58, v70
	v_mul_f32_e32 v42, v42, v71
	v_mul_f32_e32 v18, v18, v71
	v_mul_f32_e32 v34, v34, v69
	v_mul_f32_e32 v50, v50, v69
	v_rcp_f32_e32 v68, v19
	v_cndmask_b32_e64 v70, 1.0, v19, s[100:101]
	v_cndmask_b32_e64 v71, v27, 1.0, s[100:101]
	v_cndmask_b32_e64 v69, 1.0, v68, s[100:101]
	v_mul_f32_e32 v59, v59, v70
	v_mul_f32_e32 v43, v43, v71
	v_mul_f32_e32 v19, v19, v71
	v_mul_f32_e32 v35, v35, v69
	v_mul_f32_e32 v51, v51, v69
	v_rcp_f32_e32 v68, v20
	v_cndmask_b32_e64 v70, 1.0, v20, s[100:101]
	v_cndmask_b32_e64 v71, v28, 1.0, s[100:101]
	v_cndmask_b32_e64 v69, 1.0, v68, s[100:101]
	v_mul_f32_e32 v60, v60, v70
	v_mul_f32_e32 v44, v44, v71
	v_mul_f32_e32 v20, v20, v71
	v_mul_f32_e32 v36, v36, v69
	v_mul_f32_e32 v52, v52, v69
	v_rcp_f32_e32 v68, v21
	v_cndmask_b32_e64 v70, 1.0, v21, s[100:101]
	v_cndmask_b32_e64 v71, v29, 1.0, s[100:101]
	v_cndmask_b32_e64 v69, 1.0, v68, s[100:101]
	v_mul_f32_e32 v61, v61, v70
	v_mul_f32_e32 v45, v45, v71
	v_mul_f32_e32 v21, v21, v71
	v_mul_f32_e32 v37, v37, v69
	v_mul_f32_e32 v53, v53, v69
	v_rcp_f32_e32 v68, v22
	v_cndmask_b32_e64 v70, 1.0, v22, s[100:101]
	v_cndmask_b32_e64 v71, v30, 1.0, s[100:101]
	v_cndmask_b32_e64 v69, 1.0, v68, s[100:101]
	v_mul_f32_e32 v62, v62, v70
	v_mul_f32_e32 v46, v46, v71
	v_mul_f32_e32 v22, v22, v71
	v_mul_f32_e32 v38, v38, v69
	v_mul_f32_e32 v54, v54, v69
	v_rcp_f32_e32 v68, v23
	v_cndmask_b32_e64 v70, 1.0, v23, s[100:101]
	v_cndmask_b32_e64 v71, v31, 1.0, s[100:101]
	v_cndmask_b32_e64 v69, 1.0, v68, s[100:101]
	v_mul_f32_e32 v63, v63, v70
	v_mul_f32_e32 v47, v47, v71
	v_mul_f32_e32 v23, v23, v71
	v_mul_f32_e32 v39, v39, v69
	v_mul_f32_e32 v55, v55, v69
	v_rcp_f32_e32 v68, v24
	v_cndmask_b32_e64 v70, 1.0, v24, s[100:101]
	v_cndmask_b32_e64 v71, v32, 1.0, s[100:101]
	v_cndmask_b32_e64 v69, 1.0, v68, s[100:101]
	v_mul_f32_e32 v64, v64, v70
	v_mul_f32_e32 v48, v48, v71
	v_mul_f32_e32 v24, v24, v71
	v_mul_f32_e32 v40, v40, v69
	v_mul_f32_e32 v56, v56, v69
	v_rcp_f32_e32 v68, v25
	v_cndmask_b32_e64 v70, 1.0, v25, s[100:101]
	v_cndmask_b32_e64 v71, v33, 1.0, s[100:101]
	v_cndmask_b32_e64 v69, 1.0, v68, s[100:101]
	v_mul_f32_e32 v65, v65, v70
	v_mul_f32_e32 v49, v49, v71
	v_mul_f32_e32 v25, v25, v71
	v_mul_f32_e32 v41, v41, v69
	v_mul_f32_e32 v57, v57, v69
	ds_write_b128 v66, v[18:21]
	ds_write_b128 v66, v[22:25] offset:16
	ds_write_b128 v66, v[34:37] offset:8192
	ds_write_b128 v66, v[38:41] offset:8208
	ds_write_b128 v66, v[42:45] offset:16384
	ds_write_b128 v66, v[46:49] offset:16400
	ds_write_b128 v66, v[50:53] offset:24576
	ds_write_b128 v66, v[54:57] offset:24592
	ds_write_b128 v66, v[58:61] offset:32768
	ds_write_b128 v66, v[62:65] offset:32784
	v_mov_b64_e32 v[238:239], v[240:241]
	v_mov_b64_e32 v[240:241], v[242:243]

; __device__ __forceinline__ float sum8(float v) { v += dpp_xor1(v); v += dpp_xor2(v); v += dpp_hmir(v); return v; }
; __device__ __forceinline__ void scan_chain(const Params& p, int l, int chain, unsigned char* lds) {
;     ...
;             auto comp = [&](int s, const StepIn& I) {
;                 const int ts = dir == 0 ? s : 31 - s;
;                 const f32x2 w[4] = {{I.w0[0], I.w0[1]}, {I.w0[2], I.w0[3]}, {I.w1[0], I.w1[1]}, {I.w1[2], I.w1[3]}};
;                 const f32x2 k[4] = {{I.k0[0], I.k0[1]}, {I.k0[2], I.k0[3]}, {I.k1[0], I.k1[1]}, {I.k1[2], I.k1[3]}};
;                 const f32x2 a[4] = {{I.a0[0], I.a0[1]}, {I.a0[2], I.a0[3]}, {I.a1[0], I.a1[1]}, {I.a1[2], I.a1[3]}};
;                 const f32x2 bb[4] = {{I.b0[0], I.b0[1]}, {I.b0[2], I.b0[3]}, {I.b1[0], I.b1[1]}, {I.b1[2], I.b1[3]}};
;                 const f32x2 r[4] = {{I.r0[0], I.r0[1]}, {I.r0[2], I.r0[3]}, {I.r1[0], I.r1[1]}, {I.r1[2], I.r1[3]}};
;                 f32x2 d0 = S0[0] * a[0] + S0[1] * a[1], d0b = S0[2] * a[2] + S0[3] * a[3];
;                 f32x2 d1 = S1[0] * a[0] + S1[1] * a[1], d1b = S1[2] * a[2] + S1[3] * a[3];
;                 d0 += d0b; d1 += d1b;
;                 const float sa0 = sum8(d0.x + d0.y), sa1 = sum8(d1.x + d1.y);
; #pragma unroll
;                 for (int e = 0; e < 4; ++e) { S0[e] = S0[e] * w[e] + bb[e] * sa0 + k[e] * I.v0; S1[e] = S1[e] * w[e] + bb[e] * sa1 + k[e] * I.v1; }
;                 f32x2 y0 = S0[0] * r[0] + S0[1] * r[1], y0b = S0[2] * r[2] + S0[3] * r[3];
;                 f32x2 y1 = S1[0] * r[0] + S1[1] * r[1], y1b = S1[2] * r[2] + S1[3] * r[3];
;                 y0 += y0b; y1 += y1b;
;                 const float ya = sum8(y0.x + y0.y), yb = sum8(y1.x + y1.y);
;                 if (cgp == 0) { yl[ts * 64 + i0] = ya; yl[ts * 64 + i1] = yb; }
.Lscan_iter:
	s_cmp_eq_u32 s2, 1
	s_cselect_b32 s13, 0, s7
	s_waitcnt lgkmcnt(1)
	v_pk_mul_f32 v[166:167], v[210:211], v[78:79] op_sel_hi:[1,0]
	ds_read_b128 v[118:121], v18 offset:16384
	v_pk_fma_f32 v[166:167], v[212:213], v[78:79], v[166:167] op_sel:[0,1,0]
	ds_read_b128 v[122:125], v18 offset:16400
	ds_read_b128 v[110:113], v18 offset:8192
	v_pk_fma_f32 v[166:167], v[214:215], v[80:81], v[166:167] op_sel_hi:[1,0,1]
	ds_read_b128 v[114:117], v18 offset:8208
	v_pk_fma_f32 v[166:167], v[216:217], v[80:81], v[166:167] op_sel:[0,1,0]
	ds_read2_b32 v[144:145], v19 offset1:8
	ds_read_b128 v[102:105], v18
	v_pk_fma_f32 v[166:167], v[218:219], v[82:83], v[166:167] op_sel_hi:[1,0,1]
	ds_read_b128 v[106:109], v18 offset:16
	v_pk_fma_f32 v[166:167], v[220:221], v[82:83], v[166:167] op_sel:[0,1,0]
	ds_read_b128 v[126:129], v18 offset:24576
	ds_read_b128 v[130:133], v18 offset:24592
	v_pk_fma_f32 v[166:167], v[222:223], v[84:85], v[166:167] op_sel_hi:[1,0,1]
	ds_read_b128 v[134:137], v18 offset:32768
	v_pk_fma_f32 v[166:167], v[224:225], v[84:85], v[166:167] op_sel:[0,1,0]
	ds_read_b128 v[138:141], v18 offset:32784
	v_pk_fma_f32 v[146:147], v[10:11], v[142:143], v[210:211] op_sel_hi:[0,1,1]
	v_pk_fma_f32 v[148:149], v[10:11], v[142:143], v[212:213] op_sel:[1,0,0]
	v_add_f32_dpp v166, v166, v166 quad_perm:[1,0,3,2] row_mask:0xf bank_mask:0xf bound_ctrl:1
	v_add_f32_dpp v167, v167, v167 quad_perm:[1,0,3,2] row_mask:0xf bank_mask:0xf bound_ctrl:1
	v_pk_fma_f32 v[150:151], v[12:13], v[142:143], v[214:215] op_sel_hi:[0,1,1]
	v_pk_fma_f32 v[152:153], v[12:13], v[142:143], v[216:217] op_sel:[1,0,0]
	v_pk_fma_f32 v[154:155], v[14:15], v[142:143], v[218:219] op_sel_hi:[0,1,1]
	v_add_f32_dpp v166, v166, v166 quad_perm:[2,3,0,1] row_mask:0xf bank_mask:0xf bound_ctrl:1
	v_add_f32_dpp v167, v167, v167 quad_perm:[2,3,0,1] row_mask:0xf bank_mask:0xf bound_ctrl:1
	v_pk_fma_f32 v[156:157], v[14:15], v[142:143], v[220:221] op_sel:[1,0,0]
	v_pk_fma_f32 v[158:159], v[16:17], v[142:143], v[222:223] op_sel_hi:[0,1,1]
	v_pk_fma_f32 v[160:161], v[16:17], v[142:143], v[224:225] op_sel:[1,0,0]
	v_add_f32_dpp v166, v166, v166 row_half_mirror row_mask:0xf bank_mask:0xf bound_ctrl:1
	v_add_f32_dpp v167, v167, v167 row_half_mirror row_mask:0xf bank_mask:0xf bound_ctrl:1
	v_pk_fma_f32 v[146:147], v[86:87], v[166:167], v[146:147] op_sel_hi:[0,1,1]
	v_pk_fma_f32 v[148:149], v[86:87], v[166:167], v[148:149] op_sel:[1,0,0]
	v_pk_mul_f32 v[170:171], v[146:147], v[94:95] op_sel_hi:[1,0]
	v_pk_fma_f32 v[150:151], v[88:89], v[166:167], v[150:151] op_sel_hi:[0,1,1]
	v_pk_fma_f32 v[170:171], v[148:149], v[94:95], v[170:171] op_sel:[0,1,0]
	v_pk_fma_f32 v[152:153], v[88:89], v[166:167], v[152:153] op_sel:[1,0,0]
	v_pk_fma_f32 v[170:171], v[150:151], v[96:97], v[170:171] op_sel_hi:[1,0,1]
	v_pk_fma_f32 v[154:155], v[90:91], v[166:167], v[154:155] op_sel_hi:[0,1,1]
	v_pk_fma_f32 v[170:171], v[152:153], v[96:97], v[170:171] op_sel:[0,1,0]
	v_pk_fma_f32 v[156:157], v[90:91], v[166:167], v[156:157] op_sel:[1,0,0]
	v_pk_fma_f32 v[170:171], v[154:155], v[98:99], v[170:171] op_sel_hi:[1,0,1]
	v_pk_fma_f32 v[158:159], v[92:93], v[166:167], v[158:159] op_sel_hi:[0,1,1]
	v_pk_fma_f32 v[170:171], v[156:157], v[98:99], v[170:171] op_sel:[0,1,0]
	v_pk_fma_f32 v[160:161], v[92:93], v[166:167], v[160:161] op_sel:[1,0,0]
	v_pk_fma_f32 v[170:171], v[158:159], v[100:101], v[170:171] op_sel_hi:[1,0,1]
	v_add_u32_e32 v18, s13, v18
	v_add_u32_e32 v19, s13, v19
	v_pk_fma_f32 v[170:171], v[160:161], v[100:101], v[170:171] op_sel:[0,1,0]
	s_waitcnt lgkmcnt(0)
; __device__ __forceinline__ void scan_chain(const Params& p, int l, int chain, unsigned char* lds) {
;     ...
;             auto ld = [&](int s, StepIn& I) {
;                 const int ts = dir == 0 ? s : 31 - s; const float* ap = arr + ts * 64 + 8 * cgp;
;                 I.w0 = *(const f32x4*)(ap); I.w1 = *(const f32x4*)(ap + 4); I.k0 = *(const f32x4*)(ap + 2048); I.k1 = *(const f32x4*)(ap + 2048 + 4);
;                 I.a0 = *(const f32x4*)(ap + 4096); I.a1 = *(const f32x4*)(ap + 4096 + 4); I.b0 = *(const f32x4*)(ap + 6144); I.b1 = *(const f32x4*)(ap + 6144 + 4);
;                 I.r0 = *(const f32x4*)(ap + 8192); I.r1 = *(const f32x4*)(ap + 8192 + 4);
;                 I.v0 = arr[5 * 2048 + ts * 64 + i0]; I.v1 = arr[5 * 2048 + ts * 64 + i1];
;             };
;             auto comp = [&](int s, const StepIn& I) {
;                 const int ts = dir == 0 ? s : 31 - s;
;                 const f32x2 w[4] = {{I.w0[0], I.w0[1]}, {I.w0[2], I.w0[3]}, {I.w1[0], I.w1[1]}, {I.w1[2], I.w1[3]}};
;                 const f32x2 k[4] = {{I.k0[0], I.k0[1]}, {I.k0[2], I.k0[3]}, {I.k1[0], I.k1[1]}, {I.k1[2], I.k1[3]}};
;                 const f32x2 a[4] = {{I.a0[0], I.a0[1]}, {I.a0[2], I.a0[3]}, {I.a1[0], I.a1[1]}, {I.a1[2], I.a1[3]}};
;                 const f32x2 bb[4] = {{I.b0[0], I.b0[1]}, {I.b0[2], I.b0[3]}, {I.b1[0], I.b1[1]}, {I.b1[2], I.b1[3]}};
;                 const f32x2 r[4] = {{I.r0[0], I.r0[1]}, {I.r0[2], I.r0[3]}, {I.r1[0], I.r1[1]}, {I.r1[2], I.r1[3]}};
;                 f32x2 d0 = S0[0] * a[0] + S0[1] * a[1], d0b = S0[2] * a[2] + S0[3] * a[3];
;                 f32x2 d1 = S1[0] * a[0] + S1[1] * a[1], d1b = S1[2] * a[2] + S1[3] * a[3];
;                 d0 += d0b; d1 += d1b;
;                 const float sa0 = sum8(d0.x + d0.y), sa1 = sum8(d1.x + d1.y);
; #pragma unroll
;                 for (int e = 0; e < 4; ++e) { S0[e] = S0[e] * w[e] + bb[e] * sa0 + k[e] * I.v0; S1[e] = S1[e] * w[e] + bb[e] * sa1 + k[e] * I.v1; }
;                 f32x2 y0 = S0[0] * r[0] + S0[1] * r[1], y0b = S0[2] * r[2] + S0[3] * r[3];
;                 f32x2 y1 = S1[0] * r[0] + S1[1] * r[1], y1b = S1[2] * r[2] + S1[3] * r[3];
;                 y0 += y0b; y1 += y1b;
;                 const float ya = sum8(y0.x + y0.y), yb = sum8(y1.x + y1.y);
;                 if (cgp == 0) { yl[ts * 64 + i0] = ya; yl[ts * 64 + i1] = yb; }
;             };
;             __builtin_amdgcn_s_setprio(3);
	v_pk_mul_f32 v[166:167], v[146:147], v[118:119] op_sel_hi:[1,0]
	ds_read_b128 v[78:81], v18 offset:16384
	v_pk_fma_f32 v[166:167], v[148:149], v[118:119], v[166:167] op_sel:[0,1,0]
	ds_read_b128 v[82:85], v18 offset:16400
	ds_read_b128 v[10:13], v18 offset:8192
	v_pk_fma_f32 v[166:167], v[150:151], v[120:121], v[166:167] op_sel_hi:[1,0,1]
	ds_read_b128 v[14:17], v18 offset:8208
	v_pk_fma_f32 v[166:167], v[152:153], v[120:121], v[166:167] op_sel:[0,1,0]
	ds_read2_b32 v[142:143], v19 offset1:8
	v_pk_fma_f32 v[166:167], v[154:155], v[122:123], v[166:167] op_sel_hi:[1,0,1]
	v_pk_fma_f32 v[166:167], v[156:157], v[122:123], v[166:167] op_sel:[0,1,0]
	ds_read_b128 v[86:89], v18 offset:24576
	ds_read_b128 v[90:93], v18 offset:24592
	v_pk_fma_f32 v[166:167], v[158:159], v[124:125], v[166:167] op_sel_hi:[1,0,1]
	ds_read_b128 v[94:97], v18 offset:32768
	v_pk_fma_f32 v[166:167], v[160:161], v[124:125], v[166:167] op_sel:[0,1,0]
	ds_read_b128 v[98:101], v18 offset:32784
	v_pk_mul_f32 v[210:211], v[110:111], v[144:145] op_sel_hi:[0,1]
	v_pk_mul_f32 v[212:213], v[110:111], v[144:145] op_sel:[1,0]
	v_add_f32_dpp v166, v166, v166 quad_perm:[1,0,3,2] row_mask:0xf bank_mask:0xf bound_ctrl:1
	v_add_f32_dpp v167, v167, v167 quad_perm:[1,0,3,2] row_mask:0xf bank_mask:0xf bound_ctrl:1
	v_pk_mul_f32 v[214:215], v[112:113], v[144:145] op_sel_hi:[0,1]
	v_pk_mul_f32 v[216:217], v[112:113], v[144:145] op_sel:[1,0]
	v_pk_mul_f32 v[218:219], v[114:115], v[144:145] op_sel_hi:[0,1]
	v_add_f32_dpp v166, v166, v166 quad_perm:[2,3,0,1] row_mask:0xf bank_mask:0xf bound_ctrl:1
	v_add_f32_dpp v167, v167, v167 quad_perm:[2,3,0,1] row_mask:0xf bank_mask:0xf bound_ctrl:1
	v_pk_mul_f32 v[220:221], v[114:115], v[144:145] op_sel:[1,0]
	v_pk_mul_f32 v[222:223], v[116:117], v[144:145] op_sel_hi:[0,1]
	v_pk_mul_f32 v[224:225], v[116:117], v[144:145] op_sel:[1,0]
	v_add_f32_dpp v166, v166, v166 row_half_mirror row_mask:0xf bank_mask:0xf bound_ctrl:1
	v_add_f32_dpp v167, v167, v167 row_half_mirror row_mask:0xf bank_mask:0xf bound_ctrl:1
	v_pk_fma_f32 v[210:211], v[146:147], v[102:103], v[210:211] op_sel_hi:[1,0,1]
	v_pk_fma_f32 v[212:213], v[148:149], v[102:103], v[212:213] op_sel:[0,1,0]
	v_pk_fma_f32 v[214:215], v[150:151], v[104:105], v[214:215] op_sel_hi:[1,0,1]
	v_pk_fma_f32 v[216:217], v[152:153], v[104:105], v[216:217] op_sel:[0,1,0]
	v_pk_fma_f32 v[218:219], v[154:155], v[106:107], v[218:219] op_sel_hi:[1,0,1]
	v_pk_fma_f32 v[220:221], v[156:157], v[106:107], v[220:221] op_sel:[0,1,0]
	v_pk_fma_f32 v[222:223], v[158:159], v[108:109], v[222:223] op_sel_hi:[1,0,1]
	v_pk_fma_f32 v[224:225], v[160:161], v[108:109], v[224:225] op_sel:[0,1,0]
	v_pk_fma_f32 v[210:211], v[126:127], v[166:167], v[210:211] op_sel_hi:[0,1,1]
	v_pk_fma_f32 v[212:213], v[126:127], v[166:167], v[212:213] op_sel:[1,0,0]
	v_pk_mul_f32 v[172:173], v[210:211], v[134:135] op_sel_hi:[1,0]
	v_pk_fma_f32 v[214:215], v[128:129], v[166:167], v[214:215] op_sel_hi:[0,1,1]
	v_pk_fma_f32 v[172:173], v[212:213], v[134:135], v[172:173] op_sel:[0,1,0]
	v_pk_fma_f32 v[216:217], v[128:129], v[166:167], v[216:217] op_sel:[1,0,0]
	v_pk_fma_f32 v[172:173], v[214:215], v[136:137], v[172:173] op_sel_hi:[1,0,1]
	v_pk_fma_f32 v[218:219], v[130:131], v[166:167], v[218:219] op_sel_hi:[0,1,1]
	v_pk_fma_f32 v[172:173], v[216:217], v[136:137], v[172:173] op_sel:[0,1,0]
	v_pk_fma_f32 v[220:221], v[130:131], v[166:167], v[220:221] op_sel:[1,0,0]
	v_pk_fma_f32 v[172:173], v[218:219], v[138:139], v[172:173] op_sel_hi:[1,0,1]
	v_pk_fma_f32 v[222:223], v[132:133], v[166:167], v[222:223] op_sel_hi:[0,1,1]
	v_pk_fma_f32 v[172:173], v[220:221], v[138:139], v[172:173] op_sel:[0,1,0]
	v_pk_fma_f32 v[224:225], v[132:133], v[166:167], v[224:225] op_sel:[1,0,0]
	v_pk_fma_f32 v[172:173], v[222:223], v[140:141], v[172:173] op_sel_hi:[1,0,1]
	v_pk_fma_f32 v[172:173], v[224:225], v[140:141], v[172:173] op_sel:[0,1,0]
	v_add_f32_dpp v168, v170, v170 row_half_mirror row_mask:0xf bank_mask:0x5 bound_ctrl:1
	v_add_f32_dpp v169, v171, v171 row_half_mirror row_mask:0xf bank_mask:0x5 bound_ctrl:1
	v_add_f32_dpp v168, v172, v172 row_half_mirror row_mask:0xf bank_mask:0xa bound_ctrl:1
	v_add_f32_dpp v169, v173, v173 row_half_mirror row_mask:0xf bank_mask:0xa bound_ctrl:1
	v_add_u32_e32 v18, s7, v18
	v_add_f32_dpp v168, v168, v168 quad_perm:[1,0,3,2] row_mask:0xf bank_mask:0xf bound_ctrl:1
	v_add_f32_dpp v169, v169, v169 quad_perm:[1,0,3,2] row_mask:0xf bank_mask:0xf bound_ctrl:1
	v_add_u32_e32 v19, s7, v19
	v_add_f32_dpp v168, v168, v168 quad_perm:[2,3,0,1] row_mask:0xf bank_mask:0xf bound_ctrl:1
	v_add_f32_dpp v169, v169, v169 quad_perm:[2,3,0,1] row_mask:0xf bank_mask:0xf bound_ctrl:1
	s_add_i32 s2, s2, -1
	s_cmp_lg_u32 s2, 0
	s_mov_b64 exec, s[14:15]
	ds_write2_b32 v20, v168, v169 offset1:8
	s_mov_b64 exec, -1
	v_add_u32_e32 v20, s12, v20
	s_cbranch_scc1 .Lscan_iter
	s_branch .LBB0_304
